# LRU conv-weight staging: scalar pointer loads + all 4 element loads in flight (was 8 serialized round trips) in both LRU instances
# baseline (speedup 1.0000x reference)
; #define LAS __attribute__((address_space(3)))
; template <bool FINAL>
; __device__ __forceinline__ void lru_wave_phase(ArgP a, int l, LAS unsigned char* lds, int gw, int NGW, int wave, int lane, int tid) {
;     LAS float* cw = (LAS float*)(lds + LRU_CW_OFF);
;     for (int i = tid; i < 5 * 384; i += NTHR) cw[i] = i < 1536 ? a->in[12][l * 1536 + i] : a->in[13][l * 384 + (i - 1536)];
;     __syncthreads();
.LBB0_507:
	v_readlane_b32 s0, v254, 55
	v_mbcnt_lo_u32_b32 v1, -1, 0
	v_mbcnt_hi_u32_b32 v1, -1, v1
	s_nop 1
	v_add_u32_e32 v2, s0, v1
	s_load_dwordx2 s[12:13], s[30:31], 0x60
	s_load_dwordx2 s[2:3], s[30:31], 0x68
	v_lshlrev_b32_e32 v3, 2, v2
	s_mul_i32 s0, s62, 0x1800
	s_mul_i32 s1, s62, 0x600
	s_waitcnt lgkmcnt(0)
	s_add_u32 s12, s12, s0
	s_addc_u32 s13, s13, 0
	s_add_u32 s2, s2, s1
	s_addc_u32 s3, s3, 0
	global_load_dword v4, v3, s[12:13]
	global_load_dword v5, v3, s[12:13] offset:2048
	s_add_u32 s12, s12, 0x1000
	s_addc_u32 s13, s13, 0
	global_load_dword v6, v3, s[12:13]
	v_cmp_gt_u32_e32 vcc, 0x180, v2
	v_add_u32_e32 v2, 0x10000, v3
	s_and_saveexec_b64 s[0:1], vcc
	global_load_dword v7, v3, s[2:3]
	s_waitcnt vmcnt(0)
	ds_write_b32 v2, v7 offset:6144
	s_or_b64 exec, exec, s[0:1]
	s_waitcnt vmcnt(0)
	ds_write_b32 v2, v4
	ds_write_b32 v2, v5 offset:2048
	ds_write_b32 v2, v6 offset:4096

; #define LAS __attribute__((address_space(3)))
; template <bool FINAL>
; __device__ __forceinline__ void lru_wave_phase(ArgP a, int l, LAS unsigned char* lds, int gw, int NGW, int wave, int lane, int tid) {
;     LAS float* cw = (LAS float*)(lds + LRU_CW_OFF);
;     for (int i = tid; i < 5 * 384; i += NTHR) cw[i] = i < 1536 ? a->in[12][l * 1536 + i] : a->in[13][l * 384 + (i - 1536)];
;     __syncthreads();
.LBB0_776:
	s_load_dwordx2 s[12:13], s[30:31], 0x60
	s_load_dwordx2 s[2:3], s[30:31], 0x68
	v_lshlrev_b32_e32 v3, 2, v1
	s_mul_i32 s0, s62, 0x1800
	s_mul_i32 s1, s62, 0x600
	s_waitcnt lgkmcnt(0)
	s_add_u32 s12, s12, s0
	s_addc_u32 s13, s13, 0
	s_add_u32 s2, s2, s1
	s_addc_u32 s3, s3, 0
	global_load_dword v4, v3, s[12:13]
	global_load_dword v5, v3, s[12:13] offset:2048
	s_add_u32 s12, s12, 0x1000
	s_addc_u32 s13, s13, 0
	global_load_dword v6, v3, s[12:13]
	v_cmp_gt_u32_e32 vcc, 0x180, v1
	v_add_u32_e32 v2, 0x10000, v3
	s_and_saveexec_b64 s[0:1], vcc
	global_load_dword v7, v3, s[2:3]
	s_waitcnt vmcnt(0)
	ds_write_b32 v2, v7 offset:6144
	s_or_b64 exec, exec, s[0:1]
	s_waitcnt vmcnt(0)
	ds_write_b32 v2, v4
	ds_write_b32 v2, v5 offset:2048
	ds_write_b32 v2, v6 offset:4096
